# scan consumer: S.a dot as two interleaved chains of 4 plus a packed add (dependency depth 5 instead of 8)
# baseline (speedup 1.0000x reference)
; __device__ __forceinline__ void scan_chain(const Params& p, int l, int chain, unsigned char* lds) {
;     ...
;             auto ld = [&](int s, StepIn& I) {
;                 const int ts = dir == 0 ? s : 31 - s; const float* ap = arr + ts * 64 + 8 * cgp;
;                 I.w0 = *(const f32x4*)(ap); I.w1 = *(const f32x4*)(ap + 4); I.k0 = *(const f32x4*)(ap + 2048); I.k1 = *(const f32x4*)(ap + 2048 + 4);
;                 I.a0 = *(const f32x4*)(ap + 4096); I.a1 = *(const f32x4*)(ap + 4096 + 4); I.b0 = *(const f32x4*)(ap + 6144); I.b1 = *(const f32x4*)(ap + 6144 + 4);
;                 I.r0 = *(const f32x4*)(ap + 8192); I.r1 = *(const f32x4*)(ap + 8192 + 4);
;                 I.v0 = arr[5 * 2048 + ts * 64 + i0]; I.v1 = arr[5 * 2048 + ts * 64 + i1];
;             };
;             auto comp = [&](int s, const StepIn& I) {
;                 const int ts = dir == 0 ? s : 31 - s;
;                 const f32x2 w[4] = {{I.w0[0], I.w0[1]}, {I.w0[2], I.w0[3]}, {I.w1[0], I.w1[1]}, {I.w1[2], I.w1[3]}};
;                 const f32x2 k[4] = {{I.k0[0], I.k0[1]}, {I.k0[2], I.k0[3]}, {I.k1[0], I.k1[1]}, {I.k1[2], I.k1[3]}};
;                 const f32x2 a[4] = {{I.a0[0], I.a0[1]}, {I.a0[2], I.a0[3]}, {I.a1[0], I.a1[1]}, {I.a1[2], I.a1[3]}};
;                 const f32x2 bb[4] = {{I.b0[0], I.b0[1]}, {I.b0[2], I.b0[3]}, {I.b1[0], I.b1[1]}, {I.b1[2], I.b1[3]}};
;                 const f32x2 r[4] = {{I.r0[0], I.r0[1]}, {I.r0[2], I.r0[3]}, {I.r1[0], I.r1[1]}, {I.r1[2], I.r1[3]}};
;                 f32x2 d0 = S0[0] * a[0] + S0[1] * a[1], d0b = S0[2] * a[2] + S0[3] * a[3];
;                 f32x2 d1 = S1[0] * a[0] + S1[1] * a[1], d1b = S1[2] * a[2] + S1[3] * a[3];
;                 d0 += d0b; d1 += d1b;
;                 const float sa0 = sum8(d0.x + d0.y), sa1 = sum8(d1.x + d1.y);
; #pragma unroll
;                 for (int e = 0; e < 4; ++e) { S0[e] = S0[e] * w[e] + bb[e] * sa0 + k[e] * I.v0; S1[e] = S1[e] * w[e] + bb[e] * sa1 + k[e] * I.v1; }
;                 f32x2 y0 = S0[0] * r[0] + S0[1] * r[1], y0b = S0[2] * r[2] + S0[3] * r[3];
;                 f32x2 y1 = S1[0] * r[0] + S1[1] * r[1], y1b = S1[2] * r[2] + S1[3] * r[3];
;                 y0 += y0b; y1 += y1b;
;                 const float ya = sum8(y0.x + y0.y), yb = sum8(y1.x + y1.y);
;                 if (cgp == 0) { yl[ts * 64 + i0] = ya; yl[ts * 64 + i1] = yb; }
;             };
.Lscan_iter:
	s_cmp_eq_u32 s2, 1
	s_cselect_b32 s13, 0, s7
	s_waitcnt lgkmcnt(1)
	v_pk_mul_f32 v[166:167], v[210:211], v[78:79] op_sel_hi:[1,0]
	ds_read_b128 v[118:121], v18 offset:16384
	v_pk_mul_f32 v[168:169], v[212:213], v[78:79] op_sel:[0,1]
	ds_read_b128 v[122:125], v18 offset:16400
	ds_read_b128 v[110:113], v18 offset:8192
	v_pk_fma_f32 v[166:167], v[214:215], v[80:81], v[166:167] op_sel_hi:[1,0,1]
	ds_read_b128 v[114:117], v18 offset:8208
	v_pk_fma_f32 v[168:169], v[216:217], v[80:81], v[168:169] op_sel:[0,1,0]
	ds_read2_b32 v[144:145], v19 offset1:8
	ds_read_b128 v[102:105], v18
	v_pk_fma_f32 v[166:167], v[218:219], v[82:83], v[166:167] op_sel_hi:[1,0,1]
	ds_read_b128 v[106:109], v18 offset:16
	v_pk_fma_f32 v[168:169], v[220:221], v[82:83], v[168:169] op_sel:[0,1,0]
	ds_read_b128 v[126:129], v18 offset:24576
	ds_read_b128 v[130:133], v18 offset:24592
	v_pk_fma_f32 v[166:167], v[222:223], v[84:85], v[166:167] op_sel_hi:[1,0,1]
	ds_read_b128 v[134:137], v18 offset:32768
	v_pk_fma_f32 v[168:169], v[224:225], v[84:85], v[168:169] op_sel:[0,1,0]
	ds_read_b128 v[138:141], v18 offset:32784
	v_pk_add_f32 v[166:167], v[166:167], v[168:169]
	v_pk_mul_f32 v[146:147], v[10:11], v[142:143] op_sel_hi:[0,1]
	v_pk_mul_f32 v[148:149], v[10:11], v[142:143] op_sel:[1,0]
	v_add_f32_dpp v166, v166, v166 quad_perm:[1,0,3,2] row_mask:0xf bank_mask:0xf bound_ctrl:1
	v_add_f32_dpp v167, v167, v167 quad_perm:[1,0,3,2] row_mask:0xf bank_mask:0xf bound_ctrl:1
	v_pk_mul_f32 v[150:151], v[12:13], v[142:143] op_sel_hi:[0,1]
	v_pk_mul_f32 v[152:153], v[12:13], v[142:143] op_sel:[1,0]
	v_pk_mul_f32 v[154:155], v[14:15], v[142:143] op_sel_hi:[0,1]
	v_add_f32_dpp v166, v166, v166 quad_perm:[2,3,0,1] row_mask:0xf bank_mask:0xf bound_ctrl:1
	v_add_f32_dpp v167, v167, v167 quad_perm:[2,3,0,1] row_mask:0xf bank_mask:0xf bound_ctrl:1
	v_pk_mul_f32 v[156:157], v[14:15], v[142:143] op_sel:[1,0]
	v_pk_mul_f32 v[158:159], v[16:17], v[142:143] op_sel_hi:[0,1]
	v_pk_mul_f32 v[160:161], v[16:17], v[142:143] op_sel:[1,0]
	v_add_f32_dpp v166, v166, v166 row_half_mirror row_mask:0xf bank_mask:0xf bound_ctrl:1
	v_add_f32_dpp v167, v167, v167 row_half_mirror row_mask:0xf bank_mask:0xf bound_ctrl:1
	v_pk_fma_f32 v[146:147], v[210:211], v[2:3], v[146:147] op_sel_hi:[1,0,1]
	v_pk_fma_f32 v[148:149], v[212:213], v[2:3], v[148:149] op_sel:[0,1,0]
	v_pk_fma_f32 v[150:151], v[214:215], v[4:5], v[150:151] op_sel_hi:[1,0,1]
	v_pk_fma_f32 v[152:153], v[216:217], v[4:5], v[152:153] op_sel:[0,1,0]
	v_pk_fma_f32 v[154:155], v[218:219], v[6:7], v[154:155] op_sel_hi:[1,0,1]
	v_pk_fma_f32 v[156:157], v[220:221], v[6:7], v[156:157] op_sel:[0,1,0]
	v_pk_fma_f32 v[158:159], v[222:223], v[8:9], v[158:159] op_sel_hi:[1,0,1]
	v_pk_fma_f32 v[160:161], v[224:225], v[8:9], v[160:161] op_sel:[0,1,0]
	v_pk_fma_f32 v[146:147], v[86:87], v[166:167], v[146:147] op_sel_hi:[0,1,1]
	v_pk_fma_f32 v[148:149], v[86:87], v[166:167], v[148:149] op_sel:[1,0,0]
	v_pk_mul_f32 v[170:171], v[146:147], v[94:95] op_sel_hi:[1,0]
	v_pk_fma_f32 v[150:151], v[88:89], v[166:167], v[150:151] op_sel_hi:[0,1,1]
	v_pk_fma_f32 v[170:171], v[148:149], v[94:95], v[170:171] op_sel:[0,1,0]
	v_pk_fma_f32 v[152:153], v[88:89], v[166:167], v[152:153] op_sel:[1,0,0]
	v_pk_fma_f32 v[170:171], v[150:151], v[96:97], v[170:171] op_sel_hi:[1,0,1]
	v_pk_fma_f32 v[154:155], v[90:91], v[166:167], v[154:155] op_sel_hi:[0,1,1]
	v_pk_fma_f32 v[170:171], v[152:153], v[96:97], v[170:171] op_sel:[0,1,0]
	v_pk_fma_f32 v[156:157], v[90:91], v[166:167], v[156:157] op_sel:[1,0,0]
	v_pk_fma_f32 v[170:171], v[154:155], v[98:99], v[170:171] op_sel_hi:[1,0,1]
	v_pk_fma_f32 v[158:159], v[92:93], v[166:167], v[158:159] op_sel_hi:[0,1,1]
	v_pk_fma_f32 v[170:171], v[156:157], v[98:99], v[170:171] op_sel:[0,1,0]
	v_pk_fma_f32 v[160:161], v[92:93], v[166:167], v[160:161] op_sel:[1,0,0]
	v_pk_fma_f32 v[170:171], v[158:159], v[100:101], v[170:171] op_sel_hi:[1,0,1]
	v_add_u32_e32 v18, s13, v18
	v_add_u32_e32 v19, s13, v19
	v_pk_fma_f32 v[170:171], v[160:161], v[100:101], v[170:171] op_sel:[0,1,0]
	s_waitcnt lgkmcnt(0)
; __device__ __forceinline__ void scan_chain(const Params& p, int l, int chain, unsigned char* lds) {
;     ...
;             auto ld = [&](int s, StepIn& I) {
;                 const int ts = dir == 0 ? s : 31 - s; const float* ap = arr + ts * 64 + 8 * cgp;
;                 I.w0 = *(const f32x4*)(ap); I.w1 = *(const f32x4*)(ap + 4); I.k0 = *(const f32x4*)(ap + 2048); I.k1 = *(const f32x4*)(ap + 2048 + 4);
;                 I.a0 = *(const f32x4*)(ap + 4096); I.a1 = *(const f32x4*)(ap + 4096 + 4); I.b0 = *(const f32x4*)(ap + 6144); I.b1 = *(const f32x4*)(ap + 6144 + 4);
;                 I.r0 = *(const f32x4*)(ap + 8192); I.r1 = *(const f32x4*)(ap + 8192 + 4);
;                 I.v0 = arr[5 * 2048 + ts * 64 + i0]; I.v1 = arr[5 * 2048 + ts * 64 + i1];
;             };
;             auto comp = [&](int s, const StepIn& I) {
;                 const int ts = dir == 0 ? s : 31 - s;
;                 const f32x2 w[4] = {{I.w0[0], I.w0[1]}, {I.w0[2], I.w0[3]}, {I.w1[0], I.w1[1]}, {I.w1[2], I.w1[3]}};
;                 const f32x2 k[4] = {{I.k0[0], I.k0[1]}, {I.k0[2], I.k0[3]}, {I.k1[0], I.k1[1]}, {I.k1[2], I.k1[3]}};
;                 const f32x2 a[4] = {{I.a0[0], I.a0[1]}, {I.a0[2], I.a0[3]}, {I.a1[0], I.a1[1]}, {I.a1[2], I.a1[3]}};
;                 const f32x2 bb[4] = {{I.b0[0], I.b0[1]}, {I.b0[2], I.b0[3]}, {I.b1[0], I.b1[1]}, {I.b1[2], I.b1[3]}};
;                 const f32x2 r[4] = {{I.r0[0], I.r0[1]}, {I.r0[2], I.r0[3]}, {I.r1[0], I.r1[1]}, {I.r1[2], I.r1[3]}};
;                 f32x2 d0 = S0[0] * a[0] + S0[1] * a[1], d0b = S0[2] * a[2] + S0[3] * a[3];
;                 f32x2 d1 = S1[0] * a[0] + S1[1] * a[1], d1b = S1[2] * a[2] + S1[3] * a[3];
;                 d0 += d0b; d1 += d1b;
;                 const float sa0 = sum8(d0.x + d0.y), sa1 = sum8(d1.x + d1.y);
; #pragma unroll
;                 for (int e = 0; e < 4; ++e) { S0[e] = S0[e] * w[e] + bb[e] * sa0 + k[e] * I.v0; S1[e] = S1[e] * w[e] + bb[e] * sa1 + k[e] * I.v1; }
;                 f32x2 y0 = S0[0] * r[0] + S0[1] * r[1], y0b = S0[2] * r[2] + S0[3] * r[3];
;                 f32x2 y1 = S1[0] * r[0] + S1[1] * r[1], y1b = S1[2] * r[2] + S1[3] * r[3];
;                 y0 += y0b; y1 += y1b;
;                 const float ya = sum8(y0.x + y0.y), yb = sum8(y1.x + y1.y);
;                 if (cgp == 0) { yl[ts * 64 + i0] = ya; yl[ts * 64 + i1] = yb; }
;             };
;             __builtin_amdgcn_s_setprio(3);
	v_pk_mul_f32 v[166:167], v[146:147], v[118:119] op_sel_hi:[1,0]
	ds_read_b128 v[78:81], v18 offset:16384
	v_pk_mul_f32 v[168:169], v[148:149], v[118:119] op_sel:[0,1]
	ds_read_b128 v[82:85], v18 offset:16400
	ds_read_b128 v[10:13], v18 offset:8192
	v_pk_fma_f32 v[166:167], v[150:151], v[120:121], v[166:167] op_sel_hi:[1,0,1]
	ds_read_b128 v[14:17], v18 offset:8208
	v_pk_fma_f32 v[168:169], v[152:153], v[120:121], v[168:169] op_sel:[0,1,0]
	ds_read2_b32 v[142:143], v19 offset1:8
	ds_read_b128 v[2:5], v18
	v_pk_fma_f32 v[166:167], v[154:155], v[122:123], v[166:167] op_sel_hi:[1,0,1]
	ds_read_b128 v[6:9], v18 offset:16
	v_pk_fma_f32 v[168:169], v[156:157], v[122:123], v[168:169] op_sel:[0,1,0]
	ds_read_b128 v[86:89], v18 offset:24576
	ds_read_b128 v[90:93], v18 offset:24592
	v_pk_fma_f32 v[166:167], v[158:159], v[124:125], v[166:167] op_sel_hi:[1,0,1]
	ds_read_b128 v[94:97], v18 offset:32768
	v_pk_fma_f32 v[168:169], v[160:161], v[124:125], v[168:169] op_sel:[0,1,0]
	ds_read_b128 v[98:101], v18 offset:32784
	v_pk_add_f32 v[166:167], v[166:167], v[168:169]
	v_pk_mul_f32 v[210:211], v[110:111], v[144:145] op_sel_hi:[0,1]
	v_pk_mul_f32 v[212:213], v[110:111], v[144:145] op_sel:[1,0]
	v_add_f32_dpp v166, v166, v166 quad_perm:[1,0,3,2] row_mask:0xf bank_mask:0xf bound_ctrl:1
	v_add_f32_dpp v167, v167, v167 quad_perm:[1,0,3,2] row_mask:0xf bank_mask:0xf bound_ctrl:1
	v_pk_mul_f32 v[214:215], v[112:113], v[144:145] op_sel_hi:[0,1]
	v_pk_mul_f32 v[216:217], v[112:113], v[144:145] op_sel:[1,0]
	v_pk_mul_f32 v[218:219], v[114:115], v[144:145] op_sel_hi:[0,1]
	v_add_f32_dpp v166, v166, v166 quad_perm:[2,3,0,1] row_mask:0xf bank_mask:0xf bound_ctrl:1
	v_add_f32_dpp v167, v167, v167 quad_perm:[2,3,0,1] row_mask:0xf bank_mask:0xf bound_ctrl:1
	v_pk_mul_f32 v[220:221], v[114:115], v[144:145] op_sel:[1,0]
	v_pk_mul_f32 v[222:223], v[116:117], v[144:145] op_sel_hi:[0,1]
	v_pk_mul_f32 v[224:225], v[116:117], v[144:145] op_sel:[1,0]
	v_add_f32_dpp v166, v166, v166 row_half_mirror row_mask:0xf bank_mask:0xf bound_ctrl:1
	v_add_f32_dpp v167, v167, v167 row_half_mirror row_mask:0xf bank_mask:0xf bound_ctrl:1
	v_pk_fma_f32 v[210:211], v[146:147], v[102:103], v[210:211] op_sel_hi:[1,0,1]
	v_pk_fma_f32 v[212:213], v[148:149], v[102:103], v[212:213] op_sel:[0,1,0]
	v_pk_fma_f32 v[214:215], v[150:151], v[104:105], v[214:215] op_sel_hi:[1,0,1]
	v_pk_fma_f32 v[216:217], v[152:153], v[104:105], v[216:217] op_sel:[0,1,0]
	v_pk_fma_f32 v[218:219], v[154:155], v[106:107], v[218:219] op_sel_hi:[1,0,1]
	v_pk_fma_f32 v[220:221], v[156:157], v[106:107], v[220:221] op_sel:[0,1,0]
	v_pk_fma_f32 v[222:223], v[158:159], v[108:109], v[222:223] op_sel_hi:[1,0,1]
	v_pk_fma_f32 v[224:225], v[160:161], v[108:109], v[224:225] op_sel:[0,1,0]
	v_pk_fma_f32 v[210:211], v[126:127], v[166:167], v[210:211] op_sel_hi:[0,1,1]
	v_pk_fma_f32 v[212:213], v[126:127], v[166:167], v[212:213] op_sel:[1,0,0]
	v_pk_mul_f32 v[172:173], v[210:211], v[134:135] op_sel_hi:[1,0]
	v_pk_fma_f32 v[214:215], v[128:129], v[166:167], v[214:215] op_sel_hi:[0,1,1]
	v_pk_fma_f32 v[172:173], v[212:213], v[134:135], v[172:173] op_sel:[0,1,0]
	v_pk_fma_f32 v[216:217], v[128:129], v[166:167], v[216:217] op_sel:[1,0,0]
	v_pk_fma_f32 v[172:173], v[214:215], v[136:137], v[172:173] op_sel_hi:[1,0,1]
	v_pk_fma_f32 v[218:219], v[130:131], v[166:167], v[218:219] op_sel_hi:[0,1,1]
	v_pk_fma_f32 v[172:173], v[216:217], v[136:137], v[172:173] op_sel:[0,1,0]
	v_pk_fma_f32 v[220:221], v[130:131], v[166:167], v[220:221] op_sel:[1,0,0]
	v_pk_fma_f32 v[172:173], v[218:219], v[138:139], v[172:173] op_sel_hi:[1,0,1]
	v_pk_fma_f32 v[222:223], v[132:133], v[166:167], v[222:223] op_sel_hi:[0,1,1]
	v_pk_fma_f32 v[172:173], v[220:221], v[138:139], v[172:173] op_sel:[0,1,0]
	v_pk_fma_f32 v[224:225], v[132:133], v[166:167], v[224:225] op_sel:[1,0,0]
	v_pk_fma_f32 v[172:173], v[222:223], v[140:141], v[172:173] op_sel_hi:[1,0,1]
	v_pk_fma_f32 v[172:173], v[224:225], v[140:141], v[172:173] op_sel:[0,1,0]
	v_add_f32_dpp v168, v170, v170 row_half_mirror row_mask:0xf bank_mask:0x5 bound_ctrl:1
	v_add_f32_dpp v169, v171, v171 row_half_mirror row_mask:0xf bank_mask:0x5 bound_ctrl:1
	v_add_f32_dpp v168, v172, v172 row_half_mirror row_mask:0xf bank_mask:0xa bound_ctrl:1
	v_add_f32_dpp v169, v173, v173 row_half_mirror row_mask:0xf bank_mask:0xa bound_ctrl:1
	v_add_u32_e32 v18, s7, v18
	v_add_f32_dpp v168, v168, v168 quad_perm:[1,0,3,2] row_mask:0xf bank_mask:0xf bound_ctrl:1
	v_add_f32_dpp v169, v169, v169 quad_perm:[1,0,3,2] row_mask:0xf bank_mask:0xf bound_ctrl:1
	v_add_u32_e32 v19, s7, v19
	v_add_f32_dpp v168, v168, v168 quad_perm:[2,3,0,1] row_mask:0xf bank_mask:0xf bound_ctrl:1
	v_add_f32_dpp v169, v169, v169 quad_perm:[2,3,0,1] row_mask:0xf bank_mask:0xf bound_ctrl:1
	s_add_i32 s2, s2, -1
	s_cmp_lg_u32 s2, 0
	s_mov_b64 exec, s[14:15]
	ds_write2_b32 v20, v168, v169 offset1:8
	s_mov_b64 exec, -1
	v_add_u32_e32 v20, s12, v20
	s_cbranch_scc1 .Lscan_iter
	s_branch .LBB0_304
